# adds: memory cross-attention epilogue issues its 16 gate loads together ahead of the last key tile instead of one exposed round trip each
# baseline (speedup 1.0000x reference)
; #define LAS __attribute__((address_space(3)))
; template <int D, int QT0>
; __device__ __forceinline__ void qk_tile(const LAS unsigned char* Ks, int KP, const bf16x8 (&qf)[2][D / 32], f32x4 (&s)[4][2], int fr, int fq, float b0, float b1) {
; #pragma unroll
;     for (int a = 0; a < 4; ++a) { s[a][0] = (f32x4){b0, b0, b0, b0}; s[a][1] = (f32x4){b1, b1, b1, b1}; }
; #pragma unroll
;     for (int a = 0; a < 4; ++a)
; #pragma unroll
;         for (int ks = 0; ks < D / 32; ++ks) { const bf16x8 kfr = *(const LAS bf16x8*)(Ks + (a * 16 + fr) * KP + (ks * 32 + fq * 8) * 2);
;             if (QT0 == 0) s[a][0] = MFMA16(kfr, qf[0][ks], s[a][0]);
;             s[a][1] = MFMA16(kfr, qf[1][ks], s[a][1]); }
; }
; template <int D, bool DIAG, int QT0>
; __device__ __forceinline__ void sm_pv_tile(f32x4 (&s)[4][2], const LAS unsigned char* Vs, int VP, f32x4 (&o)[D / 16][2], f32x4 (&ol)[2], int fr, int fq, int keyl0, int qla, int qlb) {
; #pragma unroll
;     for (int qt = QT0; qt < 2; ++qt) {
;         if (DIAG) {
;             const int ql = (qt == 0 ? qla : qlb) + fr - keyl0 - fq * 4;
; #pragma unroll
;             for (int a = 0; a < 4; ++a)
; #pragma unroll
;                 for (int jj = 0; jj < 4; ++jj) s[a][qt][jj] = (a * 16 + jj > ql) ? -1e30f : s[a][qt][jj];
;         }
; #pragma unroll
;         for (int a = 0; a < 4; ++a)
; #pragma unroll
;             for (int jj = 0; jj < 4; ++jj) s[a][qt][jj] = ex2(s[a][qt][jj]);
;     }
; #pragma unroll
;     for (int kst = 0; kst < 2; ++kst) {
;         bf16x8 pb[2];
; #pragma unroll
;         for (int qt = QT0; qt < 2; ++qt) { u32x4 pw; pw.x = pk2(s[2 * kst][qt][0], s[2 * kst][qt][1]); pw.y = pk2(s[2 * kst][qt][2], s[2 * kst][qt][3]);
;             pw.z = pk2(s[2 * kst + 1][qt][0], s[2 * kst + 1][qt][1]); pw.w = pk2(s[2 * kst + 1][qt][2], s[2 * kst + 1][qt][3]); pb[qt] = __builtin_bit_cast(bf16x8, pw); }
;         if (QT0 == 0) ol[0] = MFMA16(ONES8, pb[0], ol[0]);
;         ol[1] = MFMA16(ONES8, pb[1], ol[1]);
; #pragma unroll
;         for (int dt = 0; dt < D / 16; ++dt) { const s16x4 lo = tr4(Vs, VP, kst * 32 + fq * 4, dt * 16, fr), hi = tr4(Vs, VP, kst * 32 + 16 + fq * 4, dt * 16, fr);
;             const bf16x8 vf = __builtin_shufflevector(lo, hi, 0, 1, 2, 3, 4, 5, 6, 7);
;             if (QT0 == 0) o[dt][0] = MFMA16(vf, pb[0], o[dt][0]);
;             o[dt][1] = MFMA16(vf, pb[1], o[dt][1]); }
;     }
.LBB0_520:
	v_lshl_add_u64 v[116:117], v[166:167], 0, s[46:47]
	v_add_co_u32_e32 v116, vcc, s34, v116
	s_bitcmp1_b32 s6, 0
	s_nop 0
	v_addc_co_u32_e32 v117, vcc, 0, v117, vcc
	global_load_dwordx4 v[128:131], v[116:117], off
	global_load_dwordx4 v[124:127], v[116:117], off offset:1024
	v_lshl_add_u64 v[116:117], v[164:165], 0, s[46:47]
	v_add_co_u32_e32 v116, vcc, s34, v116
	s_cselect_b32 s4, 0x8c00, 0
	s_nop 0
	v_addc_co_u32_e32 v117, vcc, 0, v117, vcc
	v_add_u32_e32 v181, s4, v176
	global_load_dwordx4 v[120:123], v[116:117], off
	s_nop 0
	global_load_dwordx4 v[116:119], v[116:117], off offset:1024
	ds_read_b128 v[132:135], v181
	ds_read_b128 v[140:143], v181 offset:64
	s_waitcnt lgkmcnt(1)
	v_mfma_f32_16x16x32_bf16 v[136:139], v[132:135], v[16:19], v[72:75]
	ds_read_b128 v[204:207], v181 offset:4416
	s_mov_b32 s70, s68
	s_mov_b32 s71, s68
	v_mfma_f32_16x16x32_bf16 v[132:135], v[132:135], v[24:27], v[72:75]
	ds_read_b128 v[212:215], v181 offset:8768
	s_mov_b32 s69, s68
	ds_read_b128 v[220:223], v181 offset:13120
	s_waitcnt lgkmcnt(3)
	v_mfma_f32_16x16x32_bf16 v[136:139], v[140:143], v[20:23], v[136:139]
	v_mfma_f32_16x16x32_bf16 v[132:135], v[140:143], v[28:31], v[132:135]
	ds_read_b128 v[140:143], v181 offset:128
	s_waitcnt lgkmcnt(0)
	v_mfma_f32_16x16x32_bf16 v[136:139], v[140:143], v[12:15], v[136:139]
	v_mfma_f32_16x16x32_bf16 v[132:135], v[140:143], v[36:39], v[132:135]
	ds_read_b128 v[140:143], v181 offset:192
	s_waitcnt lgkmcnt(0)
	v_mfma_f32_16x16x32_bf16 v[136:139], v[140:143], v[8:11], v[136:139]
	s_nop 7
	v_exp_f32_e32 v136, v136
	v_mfma_f32_16x16x32_bf16 v[132:135], v[140:143], v[32:35], v[132:135]
	ds_read_b128 v[140:143], v181 offset:4352
	v_exp_f32_e32 v137, v137
	v_exp_f32_e32 v138, v138
	s_waitcnt lgkmcnt(0)
	v_mfma_f32_16x16x32_bf16 v[200:203], v[140:143], v[16:19], v[72:75]
	v_exp_f32_e32 v139, v139
	v_mfma_f32_16x16x32_bf16 v[140:143], v[140:143], v[24:27], v[72:75]
	v_mfma_f32_16x16x32_bf16 v[200:203], v[204:207], v[20:23], v[200:203]
	v_mfma_f32_16x16x32_bf16 v[140:143], v[204:207], v[28:31], v[140:143]
	ds_read_b128 v[204:207], v181 offset:4480
	s_waitcnt lgkmcnt(0)
	v_mfma_f32_16x16x32_bf16 v[200:203], v[204:207], v[12:15], v[200:203]
	v_mfma_f32_16x16x32_bf16 v[140:143], v[204:207], v[36:39], v[140:143]
	ds_read_b128 v[204:207], v181 offset:4544
	s_waitcnt lgkmcnt(0)
	v_mfma_f32_16x16x32_bf16 v[200:203], v[204:207], v[8:11], v[200:203]
	s_nop 7
	v_exp_f32_e32 v225, v201
	v_mfma_f32_16x16x32_bf16 v[140:143], v[204:207], v[32:35], v[140:143]
	ds_read_b128 v[204:207], v181 offset:8704
	v_exp_f32_e32 v226, v202
	v_exp_f32_e32 v227, v203
	s_waitcnt lgkmcnt(0)
	v_mfma_f32_16x16x32_bf16 v[208:211], v[204:207], v[16:19], v[72:75]
	v_exp_f32_e32 v224, v200
	s_nop 1
	v_exp_f32_e32 v140, v140
	v_exp_f32_e32 v141, v141
	v_mfma_f32_16x16x32_bf16 v[204:207], v[204:207], v[24:27], v[72:75]
	v_exp_f32_e32 v142, v142
	v_exp_f32_e32 v143, v143
	v_mfma_f32_16x16x32_bf16 v[208:211], v[212:215], v[20:23], v[208:211]
	v_mfma_f32_16x16x32_bf16 v[204:207], v[212:215], v[28:31], v[204:207]
	ds_read_b128 v[212:215], v181 offset:8832
	s_waitcnt lgkmcnt(0)
	v_mfma_f32_16x16x32_bf16 v[208:211], v[212:215], v[12:15], v[208:211]
	v_mfma_f32_16x16x32_bf16 v[204:207], v[212:215], v[36:39], v[204:207]
	ds_read_b128 v[212:215], v181 offset:8896
	s_waitcnt lgkmcnt(0)
	v_mfma_f32_16x16x32_bf16 v[208:211], v[212:215], v[8:11], v[208:211]
	s_nop 7
	v_exp_f32_e32 v200, v211
	v_mfma_f32_16x16x32_bf16 v[212:215], v[212:215], v[32:35], v[204:207]
	v_exp_f32_e32 v182, v209
	v_exp_f32_e32 v183, v210
	s_nop 0
	ds_read_b128 v[204:207], v181 offset:13056
	s_waitcnt lgkmcnt(0)
	v_mfma_f32_16x16x32_bf16 v[216:219], v[204:207], v[16:19], v[72:75]
	v_mfma_f32_16x16x32_bf16 v[204:207], v[204:207], v[24:27], v[72:75]
	v_mfma_f32_16x16x32_bf16 v[216:219], v[220:223], v[20:23], v[216:219]
	v_mfma_f32_16x16x32_bf16 v[204:207], v[220:223], v[28:31], v[204:207]
	ds_read_b128 v[220:223], v181 offset:13184
	s_waitcnt lgkmcnt(0)
	v_mfma_f32_16x16x32_bf16 v[216:219], v[220:223], v[12:15], v[216:219]
	v_mfma_f32_16x16x32_bf16 v[204:207], v[220:223], v[36:39], v[204:207]
	ds_read_b128 v[220:223], v181 offset:13248
	v_exp_f32_e32 v181, v208
	v_exp_f32_e32 v208, v215
	s_waitcnt lgkmcnt(0)
	v_mfma_f32_16x16x32_bf16 v[216:219], v[220:223], v[8:11], v[216:219]
	s_nop 7
	v_exp_f32_e32 v201, v216
	v_mfma_f32_16x16x32_bf16 v[220:223], v[220:223], v[32:35], v[204:207]
	v_exp_f32_e32 v202, v217
	v_exp_f32_e32 v203, v218
	v_exp_f32_e32 v216, v132
	v_exp_f32_e32 v204, v219
	v_exp_f32_e32 v217, v133
	v_exp_f32_e32 v218, v134
	v_exp_f32_e32 v219, v135
	v_exp_f32_e32 v206, v213
	v_add_u32_e32 v213, s4, v172
	v_exp_f32_e32 v211, v222
	v_add_u32_e32 v222, v213, v170
	v_exp_f32_e32 v207, v214
	v_exp_f32_e32 v209, v220
	v_exp_f32_e32 v210, v221
	v_cvt_pk_bf16_f32 v132, v136, v137
	v_cvt_pk_bf16_f32 v136, v216, v217
	v_cvt_pk_bf16_f32 v137, v218, v219
	ds_read_b64_tr_b16 v[216:217], v222 offset:22016
	ds_read_b64_tr_b16 v[214:215], v222 offset:17408
	ds_read_b64_tr_b16 v[218:219], v222 offset:17440
	ds_read_b64_tr_b16 v[220:221], v222 offset:22048
	v_cvt_pk_bf16_f32 v133, v138, v139
	v_cvt_pk_bf16_f32 v134, v224, v225
	v_cvt_pk_bf16_f32 v135, v226, v227
	v_cvt_pk_bf16_f32 v138, v140, v141
	v_cvt_pk_bf16_f32 v139, v142, v143
	s_waitcnt lgkmcnt(2)
	v_mfma_f32_16x16x32_bf16 v[84:87], v[214:217], v[132:135], v[84:87]
	v_mov_b64_e32 v[142:143], s[70:71]
	v_mov_b64_e32 v[140:141], s[68:69]
	v_exp_f32_e32 v205, v212
	v_mfma_f32_16x16x32_bf16 v[88:91], v[214:217], v[136:139], v[88:91]
	ds_read_b64_tr_b16 v[214:215], v222 offset:17472
	ds_read_b64_tr_b16 v[216:217], v222 offset:22080
	v_exp_f32_e32 v212, v223
	s_andn2_b32 s4, 1, s6
	s_waitcnt lgkmcnt(2)
; __device__ __forceinline__ unsigned pk2(float lo, float hi) { f32x2_t v = {lo, hi}; bf16x2_t b = __builtin_convertvector(v, bf16x2_t); return __builtin_bit_cast(unsigned, b); }
; #define MFMA16(a, b, c) __builtin_amdgcn_mfma_f32_16x16x32_bf16((a), (b), (c), 0, 0, 0)
; template <int D, bool DIAG, int QT0>
; __device__ __forceinline__ void sm_pv_tile(f32x4 (&s)[4][2], const LAS unsigned char* Vs, int VP, f32x4 (&o)[D / 16][2], f32x4 (&ol)[2], int fr, int fq, int keyl0, int qla, int qlb) {
;     ...
;     for (int kst = 0; kst < 2; ++kst) {
;         bf16x8 pb[2];
; #pragma unroll
;         for (int qt = QT0; qt < 2; ++qt) { u32x4 pw; pw.x = pk2(s[2 * kst][qt][0], s[2 * kst][qt][1]); pw.y = pk2(s[2 * kst][qt][2], s[2 * kst][qt][3]);
;             pw.z = pk2(s[2 * kst + 1][qt][0], s[2 * kst + 1][qt][1]); pw.w = pk2(s[2 * kst + 1][qt][2], s[2 * kst + 1][qt][3]); pb[qt] = __builtin_bit_cast(bf16x8, pw); }
;         if (QT0 == 0) ol[0] = MFMA16(ONES8, pb[0], ol[0]);
;         ol[1] = MFMA16(ONES8, pb[1], ol[1]);
; #pragma unroll
;         for (int dt = 0; dt < D / 16; ++dt) { const s16x4 lo = tr4(Vs, VP, kst * 32 + fq * 4, dt * 16, fr), hi = tr4(Vs, VP, kst * 32 + 16 + fq * 4, dt * 16, fr);
;             const bf16x8 vf = __builtin_shufflevector(lo, hi, 0, 1, 2, 3, 4, 5, 6, 7);
;             if (QT0 == 0) o[dt][0] = MFMA16(vf, pb[0], o[dt][0]);
;             o[dt][1] = MFMA16(vf, pb[1], o[dt][1]); }
;     }
	v_mfma_f32_16x16x32_bf16 v[92:95], v[218:221], v[132:135], v[92:95]
	s_mul_i32 s4, s4, 0x8c00
	s_add_i32 s6, s6, 1
	s_add_u32 s46, s46, 0x20000
	v_mfma_f32_16x16x32_bf16 v[96:99], v[218:221], v[136:139], v[96:99]
	v_add_u32_e32 v218, v213, v169
	v_add_u32_e32 v213, v213, v168
	s_addc_u32 s47, s47, 0
	s_waitcnt lgkmcnt(0)
	v_mfma_f32_16x16x32_bf16 v[76:79], v[214:217], v[132:135], v[76:79]
	s_cmp_lg_u32 s46, 0x60000
	v_mfma_f32_16x16x32_bf16 v[80:83], v[214:217], v[136:139], v[80:83]
	ds_read_b64_tr_b16 v[214:215], v218 offset:17408
	ds_read_b64_tr_b16 v[216:217], v218 offset:22016
	s_waitcnt lgkmcnt(0)
	v_mfma_f32_16x16x32_bf16 v[100:103], v[214:217], v[132:135], v[100:103]
	v_mfma_f32_16x16x32_bf16 v[104:107], v[214:217], v[136:139], v[104:107]
	ds_read_b64_tr_b16 v[214:215], v222 offset:17536
	ds_read_b64_tr_b16 v[216:217], v222 offset:22144
	s_waitcnt lgkmcnt(0)
	v_mfma_f32_16x16x32_bf16 v[64:67], v[214:217], v[132:135], v[64:67]
	v_mfma_f32_16x16x32_bf16 v[68:71], v[214:217], v[136:139], v[68:71]
	ds_read_b64_tr_b16 v[214:215], v222 offset:17568
	ds_read_b64_tr_b16 v[216:217], v222 offset:22176
	s_waitcnt lgkmcnt(0)
	v_mfma_f32_16x16x32_bf16 v[56:59], v[214:217], v[132:135], v[56:59]
	v_mfma_f32_16x16x32_bf16 v[60:63], v[214:217], v[136:139], v[60:63]
	ds_read_b64_tr_b16 v[214:215], v222 offset:17600
	ds_read_b64_tr_b16 v[216:217], v222 offset:22208
	s_waitcnt lgkmcnt(0)
	v_mfma_f32_16x16x32_bf16 v[48:51], v[214:217], v[132:135], v[48:51]
	v_mfma_f32_16x16x32_bf16 v[52:55], v[214:217], v[136:139], v[52:55]
	ds_read_b64_tr_b16 v[214:215], v213 offset:17408
	ds_read_b64_tr_b16 v[216:217], v213 offset:22016
	v_mfma_f32_16x16x32_bf16 v[108:111], v[140:143], v[132:135], v[108:111]
	v_mfma_f32_16x16x32_bf16 v[112:115], v[140:143], v[136:139], v[112:115]
	s_waitcnt lgkmcnt(0)
	v_mfma_f32_16x16x32_bf16 v[40:43], v[214:217], v[132:135], v[40:43]
	v_cvt_pk_bf16_f32 v132, v181, v182
	v_cvt_pk_bf16_f32 v133, v183, v200
	v_cvt_pk_bf16_f32 v134, v201, v202
	v_mfma_f32_16x16x32_bf16 v[44:47], v[214:217], v[136:139], v[44:47]
	v_cvt_pk_bf16_f32 v135, v203, v204
	v_cvt_pk_bf16_f32 v136, v205, v206
	v_cvt_pk_bf16_f32 v137, v207, v208
	v_cvt_pk_bf16_f32 v138, v209, v210
	v_cvt_pk_bf16_f32 v139, v211, v212
	v_mfma_f32_16x16x32_bf16 v[108:111], v[140:143], v[132:135], v[108:111]
	v_add_u32_e32 v181, s4, v173
	v_mfma_f32_16x16x32_bf16 v[112:115], v[140:143], v[136:139], v[112:115]
	ds_read_b64_tr_b16 v[140:141], v222 offset:26624
	ds_read_b64_tr_b16 v[142:143], v222 offset:31232
	s_waitcnt lgkmcnt(0)
	v_mfma_f32_16x16x32_bf16 v[84:87], v[140:143], v[132:135], v[84:87]
	v_mfma_f32_16x16x32_bf16 v[88:91], v[140:143], v[136:139], v[88:91]
	ds_read_b64_tr_b16 v[140:141], v222 offset:26656
	ds_read_b64_tr_b16 v[142:143], v222 offset:31264
	s_waitcnt lgkmcnt(0)
	v_mfma_f32_16x16x32_bf16 v[92:95], v[140:143], v[132:135], v[92:95]
	v_mfma_f32_16x16x32_bf16 v[96:99], v[140:143], v[136:139], v[96:99]
	ds_read_b64_tr_b16 v[140:141], v222 offset:26688
	ds_read_b64_tr_b16 v[142:143], v222 offset:31296
	s_waitcnt lgkmcnt(0)
	v_mfma_f32_16x16x32_bf16 v[76:79], v[140:143], v[132:135], v[76:79]
	v_mfma_f32_16x16x32_bf16 v[80:83], v[140:143], v[136:139], v[80:83]
	ds_read_b64_tr_b16 v[140:141], v218 offset:26624
	ds_read_b64_tr_b16 v[142:143], v218 offset:31232
	s_waitcnt lgkmcnt(0)
	v_mfma_f32_16x16x32_bf16 v[100:103], v[140:143], v[132:135], v[100:103]
	v_mfma_f32_16x16x32_bf16 v[104:107], v[140:143], v[136:139], v[104:107]
	ds_read_b64_tr_b16 v[140:141], v222 offset:26752
	ds_read_b64_tr_b16 v[142:143], v222 offset:31360
	s_waitcnt lgkmcnt(0)
	v_mfma_f32_16x16x32_bf16 v[64:67], v[140:143], v[132:135], v[64:67]
	v_mfma_f32_16x16x32_bf16 v[68:71], v[140:143], v[136:139], v[68:71]
	ds_read_b64_tr_b16 v[140:141], v222 offset:26784
	ds_read_b64_tr_b16 v[142:143], v222 offset:31392
	s_waitcnt lgkmcnt(0)
	v_mfma_f32_16x16x32_bf16 v[56:59], v[140:143], v[132:135], v[56:59]
	v_mfma_f32_16x16x32_bf16 v[60:63], v[140:143], v[136:139], v[60:63]
	ds_read_b64_tr_b16 v[140:141], v222 offset:26816
	ds_read_b64_tr_b16 v[142:143], v222 offset:31424
	s_waitcnt lgkmcnt(0)
	v_mfma_f32_16x16x32_bf16 v[48:51], v[140:143], v[132:135], v[48:51]
	v_mfma_f32_16x16x32_bf16 v[52:55], v[140:143], v[136:139], v[52:55]
	ds_read_b64_tr_b16 v[140:141], v213 offset:26624
	ds_read_b64_tr_b16 v[142:143], v213 offset:31232
	s_waitcnt lgkmcnt(0)
	v_mfma_f32_16x16x32_bf16 v[40:43], v[140:143], v[132:135], v[40:43]
	s_waitcnt vmcnt(3)
	v_lshlrev_b32_e32 v132, 16, v131
	v_and_b32_e32 v133, 0xffff0000, v131
	v_pk_mul_f32 v[134:135], v[132:133], v[132:133]
	v_mfma_f32_16x16x32_bf16 v[44:47], v[140:143], v[136:139], v[44:47]
	v_lshlrev_b32_e32 v142, 16, v128
	v_and_b32_e32 v143, 0xffff0000, v128
	v_lshlrev_b32_e32 v138, 16, v129
	v_and_b32_e32 v139, 0xffff0000, v129
	v_pk_mul_f32 v[128:129], v[142:143], v[142:143]
	v_pk_mul_f32 v[140:141], v[138:139], v[138:139]
	v_add_f32_e32 v128, v128, v129
	v_lshlrev_b32_e32 v136, 16, v130
	v_and_b32_e32 v137, 0xffff0000, v130
	v_add_f32_e32 v128, v140, v128
	v_pk_mul_f32 v[130:131], v[136:137], v[136:137]
	v_add_f32_e32 v128, v141, v128
	v_add_f32_e32 v128, v130, v128
	v_add_f32_e32 v128, v131, v128
	v_add_f32_e32 v128, v134, v128
	v_add_f32_e32 v128, v135, v128
	ds_bpermute_b32 v129, v171, v128
	s_waitcnt lgkmcnt(0)
	v_add_f32_e32 v128, v128, v129
	ds_bpermute_b32 v129, v195, v128
	s_waitcnt lgkmcnt(0)
	v_add_f32_e32 v128, v128, v129
	ds_bpermute_b32 v129, v196, v128
	s_waitcnt lgkmcnt(0)
	v_add_f32_e32 v128, v128, v129
	ds_bpermute_b32 v129, v197, v128
	s_waitcnt lgkmcnt(0)
; __device__ __forceinline__ float frcp(float x) { return __builtin_amdgcn_rcpf(x); }
; #define BAR_LDS() do { asm volatile("s_waitcnt lgkmcnt(0)" ::: "memory"); __builtin_amdgcn_s_barrier(); asm volatile("" ::: "memory"); } while (0)
; #define MEM_LOAD(kt) do { _Pragma("unroll") for (int ii = 0; ii < 2; ++ii) { const int cid = tid + 512 * ii; \
;         ukr[ii] = *(const u32x4*)(kvm + (size_t)((kt) * 64 + (cid >> 4)) * 1024 + hm * 128 + (cid & 15) * 8); \
;         uvr[ii] = *(const u32x4*)(kvm + (size_t)((kt) * 64 + (cid >> 4)) * 1024 + 512 + hm * 128 + (cid & 15) * 8); } } while (0)
; __device__ __forceinline__ void mem_unit(const Args& a, int l, LAS unsigned char* lds, int b, int hm, int qb) {
;     ...
;     MEM_STORE(0);
;     BAR_LDS();
;     for (int kt = 0; kt < 4; ++kt) {
;         if (kt < 3) MEM_LOAD(kt + 1);
;         attn_tile<128, false, 0>(Ks + (kt & 1) * 35840, 272, Vs + (kt & 1) * 35840, 288, qf, o, ol, fr, fq, 0, 0, 0, -gm, -gm);
;         if (kt < 3) MEM_STORE((kt + 1) & 1);
;         BAR_LDS();
;     }
;     ...
; #pragma unroll
;     for (int qt = 0; qt < 2; ++qt) {
;         const float inv = frcp(ol[qt][0]);
;         const size_t row = rowbase + q0 + qt * 16 + fr;
; #pragma unroll
;         for (int dt = 0; dt < 8; ++dt) { const int d0 = dt * 16 + fq * 4;
;             const u32x2 z = *(const u32x2*)(proj + row * NCOL + CZ + 1024 + hm * 128 + d0);
	v_add_f32_e32 v128, v128, v129
	v_fmamk_f32 v128, v128, 0x3c000000, v186
	v_rsq_f32_e32 v134, v128
	s_nop 0
	v_pk_mul_f32 v[128:129], v[134:135], v[142:143] op_sel_hi:[0,1]
	v_pk_mul_f32 v[130:131], v[134:135], v[138:139] op_sel_hi:[0,1]
	v_pk_mul_f32 v[128:129], v[4:5], v[128:129]
	v_pk_mul_f32 v[130:131], v[6:7], v[130:131]
	v_cvt_pk_bf16_f32 v128, v128, v129
	v_cvt_pk_bf16_f32 v129, v130, v131
	v_pk_mul_f32 v[130:131], v[134:135], v[136:137] op_sel_hi:[0,1]
	v_pk_mul_f32 v[132:133], v[134:135], v[132:133] op_sel_hi:[0,1]
	v_pk_mul_f32 v[130:131], v[0:1], v[130:131]
	v_pk_mul_f32 v[132:133], v[2:3], v[132:133]
	v_cvt_pk_bf16_f32 v130, v130, v131
	v_cvt_pk_bf16_f32 v131, v132, v133
	v_add_u32_e32 v132, v181, v174
	s_waitcnt vmcnt(1)
	v_lshlrev_b32_e32 v134, 16, v120
	v_and_b32_e32 v135, 0xffff0000, v120
	ds_write_b128 v132, v[128:131]
	v_lshlrev_b32_e32 v130, 16, v121
	v_and_b32_e32 v131, 0xffff0000, v121
	v_pk_mul_f32 v[120:121], v[134:135], v[134:135]
	v_add_u32_e32 v128, v181, v175
	v_pk_mul_f32 v[132:133], v[130:131], v[130:131]
	v_add_f32_e32 v120, v120, v121
	ds_write_b128 v128, v[124:127] offset:17408
	v_lshlrev_b32_e32 v128, 16, v122
	v_and_b32_e32 v129, 0xffff0000, v122
	v_add_f32_e32 v120, v132, v120
	v_lshlrev_b32_e32 v124, 16, v123
	v_and_b32_e32 v125, 0xffff0000, v123
	v_pk_mul_f32 v[122:123], v[128:129], v[128:129]
	v_add_f32_e32 v120, v133, v120
	v_add_f32_e32 v120, v122, v120
	v_pk_mul_f32 v[126:127], v[124:125], v[124:125]
	v_add_f32_e32 v120, v123, v120
	v_add_f32_e32 v120, v126, v120
	v_add_f32_e32 v120, v127, v120
	ds_bpermute_b32 v121, v171, v120
	s_waitcnt lgkmcnt(0)
	v_add_f32_e32 v120, v120, v121
	ds_bpermute_b32 v121, v195, v120
	s_waitcnt lgkmcnt(0)
	v_add_f32_e32 v120, v120, v121
	ds_bpermute_b32 v121, v196, v120
	s_waitcnt lgkmcnt(0)
	v_add_f32_e32 v120, v120, v121
	ds_bpermute_b32 v121, v197, v120
	s_waitcnt lgkmcnt(0)
	v_add_f32_e32 v120, v120, v121
	v_fmamk_f32 v120, v120, 0x3c000000, v186
	v_rsq_f32_e32 v126, v120
	s_nop 0
	v_pk_mul_f32 v[120:121], v[126:127], v[134:135] op_sel_hi:[0,1]
	v_pk_mul_f32 v[122:123], v[126:127], v[130:131] op_sel_hi:[0,1]
	v_pk_mul_f32 v[120:121], v[4:5], v[120:121]
	v_pk_mul_f32 v[122:123], v[6:7], v[122:123]
	v_cvt_pk_bf16_f32 v120, v120, v121
	v_cvt_pk_bf16_f32 v121, v122, v123
	v_pk_mul_f32 v[122:123], v[126:127], v[128:129] op_sel_hi:[0,1]
	v_pk_mul_f32 v[124:125], v[126:127], v[124:125] op_sel_hi:[0,1]
	v_pk_mul_f32 v[122:123], v[0:1], v[122:123]
	v_pk_mul_f32 v[124:125], v[2:3], v[124:125]
	v_cvt_pk_bf16_f32 v122, v122, v123
	v_cvt_pk_bf16_f32 v123, v124, v125
	v_add_u32_e32 v124, v181, v177
	ds_write_b128 v124, v[120:123]
	v_add_u32_e32 v120, v181, v180
	s_waitcnt vmcnt(0)
	ds_write_b128 v120, v[116:119] offset:17408
	s_waitcnt lgkmcnt(0)
	s_barrier
	s_cbranch_scc1 .LBB0_520
	ds_read_b128 v[0:3], v176 offset:35840
	ds_read_b128 v[118:121], v176 offset:35904
	v_add_u32_e32 v141, v172, v170
	v_add_u32_e32 v116, 0x4400, v172
	s_lshl_b32 s6, s8, 1
	v_lshlrev_b32_e32 v144, 1, v144
	s_mov_b64 s[4:5], 0x1400
	v_lshl_add_u64 v[164:165], v[162:163], 0, s[6:7]
	v_lshl_add_u64 v[166:167], v[158:159], 0, s[6:7]
	v_lshl_add_u64 v[164:165], v[164:165], 0, v[144:145]
	v_lshl_add_u64 v[166:167], v[166:167], 0, v[144:145]
	v_lshl_add_u64 v[164:165], v[164:165], 0, s[4:5]
	v_lshl_add_u64 v[166:167], v[166:167], 0, s[4:5]
	global_load_dwordx2 v[200:201], v[164:165], off
	global_load_dwordx2 v[202:203], v[164:165], off offset:32
	global_load_dwordx2 v[204:205], v[164:165], off offset:64
	global_load_dwordx2 v[206:207], v[164:165], off offset:96
	global_load_dwordx2 v[208:209], v[164:165], off offset:128
	global_load_dwordx2 v[210:211], v[164:165], off offset:160
	global_load_dwordx2 v[212:213], v[164:165], off offset:192
	global_load_dwordx2 v[214:215], v[164:165], off offset:224
	global_load_dwordx2 v[216:217], v[166:167], off
	global_load_dwordx2 v[218:219], v[166:167], off offset:32
	global_load_dwordx2 v[220:221], v[166:167], off offset:64
	global_load_dwordx2 v[222:223], v[166:167], off offset:96
	global_load_dwordx2 v[224:225], v[166:167], off offset:128
	global_load_dwordx2 v[226:227], v[166:167], off offset:160
	global_load_dwordx2 v[228:229], v[166:167], off offset:192
	global_load_dwordx2 v[230:231], v[166:167], off offset:224
	s_add_i32 s14, s14, s3
	s_cmpk_gt_i32 s14, 0xff
	s_waitcnt lgkmcnt(1)
	v_mfma_f32_16x16x32_bf16 v[4:7], v[0:3], v[16:19], v[72:75]
	ds_read_b128 v[126:129], v176 offset:40256
	ds_read_b128 v[134:137], v176 offset:44608
	v_mfma_f32_16x16x32_bf16 v[0:3], v[0:3], v[24:27], v[72:75]
	s_waitcnt lgkmcnt(2)
	v_mfma_f32_16x16x32_bf16 v[4:7], v[118:121], v[20:23], v[4:7]
	v_mfma_f32_16x16x32_bf16 v[0:3], v[118:121], v[28:31], v[0:3]
	ds_read_b128 v[118:121], v176 offset:35968
	s_waitcnt lgkmcnt(0)
	v_mfma_f32_16x16x32_bf16 v[4:7], v[118:121], v[12:15], v[4:7]
	v_mfma_f32_16x16x32_bf16 v[0:3], v[118:121], v[36:39], v[0:3]
	ds_read_b128 v[118:121], v176 offset:36032
	s_waitcnt lgkmcnt(0)
	v_mfma_f32_16x16x32_bf16 v[4:7], v[118:121], v[8:11], v[4:7]
	s_nop 7
	v_exp_f32_e32 v4, v4
	v_mfma_f32_16x16x32_bf16 v[0:3], v[118:121], v[32:35], v[0:3]
	ds_read_b128 v[118:121], v176 offset:40192
	v_exp_f32_e32 v5, v5
	v_exp_f32_e32 v6, v6
	s_waitcnt lgkmcnt(0)
	v_mfma_f32_16x16x32_bf16 v[122:125], v[118:121], v[16:19], v[72:75]
	v_exp_f32_e32 v7, v7
	s_nop 1
	v_exp_f32_e32 v0, v0
	v_exp_f32_e32 v1, v1
	v_mfma_f32_16x16x32_bf16 v[118:121], v[118:121], v[24:27], v[72:75]
	v_exp_f32_e32 v2, v2
	v_exp_f32_e32 v3, v3
	v_mfma_f32_16x16x32_bf16 v[122:125], v[126:129], v[20:23], v[122:125]
	v_mfma_f32_16x16x32_bf16 v[118:121], v[126:129], v[28:31], v[118:121]
	ds_read_b128 v[126:129], v176 offset:40320
	s_waitcnt lgkmcnt(0)
; #define LAS __attribute__((address_space(3)))
; template <int D, int QT0>
; __device__ __forceinline__ void qk_tile(const LAS unsigned char* Ks, int KP, const bf16x8 (&qf)[2][D / 32], f32x4 (&s)[4][2], int fr, int fq, float b0, float b1) {
; #pragma unroll
;     for (int a = 0; a < 4; ++a) { s[a][0] = (f32x4){b0, b0, b0, b0}; s[a][1] = (f32x4){b1, b1, b1, b1}; }
; #pragma unroll
;     for (int a = 0; a < 4; ++a)
; #pragma unroll
;         for (int ks = 0; ks < D / 32; ++ks) { const bf16x8 kfr = *(const LAS bf16x8*)(Ks + (a * 16 + fr) * KP + (ks * 32 + fq * 8) * 2);
;             if (QT0 == 0) s[a][0] = MFMA16(kfr, qf[0][ks], s[a][0]);
;             s[a][1] = MFMA16(kfr, qf[1][ks], s[a][1]); }
; }
; template <int D, bool DIAG, int QT0>
; __device__ __forceinline__ void sm_pv_tile(f32x4 (&s)[4][2], const LAS unsigned char* Vs, int VP, f32x4 (&o)[D / 16][2], f32x4 (&ol)[2], int fr, int fq, int keyl0, int qla, int qlb) {
; #pragma unroll
;     for (int qt = QT0; qt < 2; ++qt) {
;         if (DIAG) {
;             const int ql = (qt == 0 ? qla : qlb) + fr - keyl0 - fq * 4;
; #pragma unroll
;             for (int a = 0; a < 4; ++a)
; #pragma unroll
;                 for (int jj = 0; jj < 4; ++jj) s[a][qt][jj] = (a * 16 + jj > ql) ? -1e30f : s[a][qt][jj];
;         }
; #pragma unroll
;         for (int a = 0; a < 4; ++a)
; #pragma unroll
;             for (int jj = 0; jj < 4; ++jj) s[a][qt][jj] = ex2(s[a][qt][jj]);
;     }
; #pragma unroll
;     for (int kst = 0; kst < 2; ++kst) {
;         bf16x8 pb[2];
; #pragma unroll
;         for (int qt = QT0; qt < 2; ++qt) { u32x4 pw; pw.x = pk2(s[2 * kst][qt][0], s[2 * kst][qt][1]); pw.y = pk2(s[2 * kst][qt][2], s[2 * kst][qt][3]);
;             pw.z = pk2(s[2 * kst + 1][qt][0], s[2 * kst + 1][qt][1]); pw.w = pk2(s[2 * kst + 1][qt][2], s[2 * kst + 1][qt][3]); pb[qt] = __builtin_bit_cast(bf16x8, pw); }
;         if (QT0 == 0) ol[0] = MFMA16(ONES8, pb[0], ol[0]);
;         ol[1] = MFMA16(ONES8, pb[1], ol[1]);
; #pragma unroll
;         for (int dt = 0; dt < D / 16; ++dt) { const s16x4 lo = tr4(Vs, VP, kst * 32 + fq * 4, dt * 16, fr), hi = tr4(Vs, VP, kst * 32 + 16 + fq * 4, dt * 16, fr);
;             const bf16x8 vf = __builtin_shufflevector(lo, hi, 0, 1, 2, 3, 4, 5, 6, 7);
;             if (QT0 == 0) o[dt][0] = MFMA16(vf, pb[0], o[dt][0]);
;             o[dt][1] = MFMA16(vf, pb[1], o[dt][1]); }
;     }
	v_mfma_f32_16x16x32_bf16 v[122:125], v[126:129], v[12:15], v[122:125]
	v_mfma_f32_16x16x32_bf16 v[118:121], v[126:129], v[36:39], v[118:121]
	ds_read_b128 v[126:129], v176 offset:40384
	s_waitcnt lgkmcnt(0)
	v_mfma_f32_16x16x32_bf16 v[122:125], v[126:129], v[8:11], v[122:125]
	v_mfma_f32_16x16x32_bf16 v[118:121], v[126:129], v[32:35], v[118:121]
	ds_read_b128 v[126:129], v176 offset:44544
	s_waitcnt lgkmcnt(0)
	v_mfma_f32_16x16x32_bf16 v[130:133], v[126:129], v[16:19], v[72:75]
	v_mfma_f32_16x16x32_bf16 v[126:129], v[126:129], v[24:27], v[72:75]
	v_mfma_f32_16x16x32_bf16 v[130:133], v[134:137], v[20:23], v[130:133]
	v_mfma_f32_16x16x32_bf16 v[126:129], v[134:137], v[28:31], v[126:129]
	ds_read_b128 v[134:137], v176 offset:44672
	s_waitcnt lgkmcnt(0)
	v_mfma_f32_16x16x32_bf16 v[130:133], v[134:137], v[12:15], v[130:133]
	v_mfma_f32_16x16x32_bf16 v[126:129], v[134:137], v[36:39], v[126:129]
	ds_read_b128 v[134:137], v176 offset:44736
	s_waitcnt lgkmcnt(0)
	v_mfma_f32_16x16x32_bf16 v[130:133], v[134:137], v[8:11], v[130:133]
	v_mfma_f32_16x16x32_bf16 v[126:129], v[134:137], v[32:35], v[126:129]
	ds_read_b128 v[134:137], v176 offset:48896
	s_waitcnt lgkmcnt(0)
	v_mfma_f32_16x16x32_bf16 v[16:19], v[134:137], v[16:19], v[72:75]
	s_nop 4
	v_exp_f32_e32 v117, v126
	v_mfma_f32_16x16x32_bf16 v[24:27], v[134:137], v[24:27], v[72:75]
	v_exp_f32_e32 v134, v127
	v_exp_f32_e32 v135, v128
	v_exp_f32_e32 v136, v129
	ds_read_b128 v[72:75], v176 offset:48960
	s_waitcnt lgkmcnt(0)
	v_mfma_f32_16x16x32_bf16 v[16:19], v[72:75], v[20:23], v[16:19]
	v_mfma_f32_16x16x32_bf16 v[20:23], v[72:75], v[28:31], v[24:27]
	s_nop 2
	ds_read_b128 v[24:27], v176 offset:49024
	s_waitcnt lgkmcnt(0)
	v_mfma_f32_16x16x32_bf16 v[12:15], v[24:27], v[12:15], v[16:19]
	v_mfma_f32_16x16x32_bf16 v[16:19], v[24:27], v[36:39], v[20:23]
	v_exp_f32_e32 v38, v132
	v_exp_f32_e32 v39, v133
	s_nop 0
	ds_read_b128 v[20:23], v176 offset:49088
	s_waitcnt lgkmcnt(0)
	v_mfma_f32_16x16x32_bf16 v[8:11], v[20:23], v[8:11], v[12:15]
	ds_read_b64_tr_b16 v[26:27], v141 offset:57856
	ds_read_b64_tr_b16 v[24:25], v141 offset:53248
	ds_read_b64_tr_b16 v[28:29], v141 offset:53280
	ds_read_b64_tr_b16 v[30:31], v141 offset:57888
	s_nop 3
	v_exp_f32_e32 v72, v8
	v_mfma_f32_16x16x32_bf16 v[12:15], v[20:23], v[32:35], v[16:19]
	v_exp_f32_e32 v73, v9
	v_exp_f32_e32 v74, v10
	v_exp_f32_e32 v75, v11
	v_exp_f32_e32 v16, v122
	v_exp_f32_e32 v17, v123
	v_exp_f32_e32 v18, v124
	v_exp_f32_e32 v19, v125
	v_exp_f32_e32 v8, v118
	v_exp_f32_e32 v9, v119
	v_exp_f32_e32 v10, v120
	v_exp_f32_e32 v11, v121
	v_exp_f32_e32 v137, v12
	v_exp_f32_e32 v138, v13
	v_exp_f32_e32 v139, v14
	v_exp_f32_e32 v140, v15
	v_cvt_pk_bf16_f32 v12, v4, v5
	v_cvt_pk_bf16_f32 v13, v6, v7
	v_cvt_pk_bf16_f32 v14, v16, v17
	v_cvt_pk_bf16_f32 v15, v18, v19
	v_cvt_pk_bf16_f32 v16, v0, v1
	v_cvt_pk_bf16_f32 v17, v2, v3
	v_cvt_pk_bf16_f32 v18, v8, v9
	v_cvt_pk_bf16_f32 v19, v10, v11
	s_waitcnt lgkmcnt(2)
	v_mfma_f32_16x16x32_bf16 v[20:23], v[24:27], v[12:15], v[84:87]
	v_mov_b64_e32 v[0:1], s[68:69]
	v_mov_b64_e32 v[2:3], s[70:71]
	v_exp_f32_e32 v32, v130
	v_mfma_f32_16x16x32_bf16 v[24:27], v[24:27], v[16:19], v[88:91]
	v_exp_f32_e32 v33, v131
	v_cvt_pk_bf16_f32 v72, v72, v73
	v_cvt_pk_bf16_f32 v73, v74, v75
	s_waitcnt lgkmcnt(0)
	v_mfma_f32_16x16x32_bf16 v[84:87], v[28:31], v[12:15], v[92:95]
	v_cvt_pk_bf16_f32 v74, v117, v134
	v_cvt_pk_bf16_f32 v75, v135, v136
	v_mfma_f32_16x16x32_bf16 v[88:91], v[28:31], v[16:19], v[96:99]
	ds_read_b64_tr_b16 v[28:29], v141 offset:53312
	ds_read_b64_tr_b16 v[30:31], v141 offset:57920
	s_waitcnt lgkmcnt(0)
	v_mfma_f32_16x16x32_bf16 v[96:99], v[28:31], v[16:19], v[80:83]
	s_nop 2
	v_add_u32_e32 v82, v172, v169
	v_add_u32_e32 v83, v172, v168
	v_mfma_f32_16x16x32_bf16 v[92:95], v[28:31], v[12:15], v[76:79]
	ds_read_b64_tr_b16 v[28:29], v82 offset:53248
	ds_read_b64_tr_b16 v[30:31], v82 offset:57856
	s_nop 0
	v_cvt_pk_bf16_f32 v76, v137, v138
	s_waitcnt lgkmcnt(0)
	v_mfma_f32_16x16x32_bf16 v[100:103], v[28:31], v[12:15], v[100:103]
	v_cvt_pk_bf16_f32 v77, v139, v140
	v_mfma_f32_16x16x32_bf16 v[104:107], v[28:31], v[16:19], v[104:107]
	ds_read_b64_tr_b16 v[28:29], v141 offset:53376
	ds_read_b64_tr_b16 v[30:31], v141 offset:57984
	v_mfma_f32_16x16x32_bf16 v[4:7], v[0:3], v[12:15], v[108:111]
	v_mfma_f32_16x16x32_bf16 v[8:11], v[0:3], v[16:19], v[112:115]
	s_waitcnt lgkmcnt(0)
	v_mfma_f32_16x16x32_bf16 v[108:111], v[28:31], v[12:15], v[64:67]
	v_mfma_f32_16x16x32_bf16 v[112:115], v[28:31], v[16:19], v[68:71]
	ds_read_b64_tr_b16 v[28:29], v141 offset:53408
	ds_read_b64_tr_b16 v[30:31], v141 offset:58016
	s_nop 0
	v_cvt_pk_bf16_f32 v70, v32, v33
	s_waitcnt lgkmcnt(0)
	v_mfma_f32_16x16x32_bf16 v[118:121], v[28:31], v[12:15], v[56:59]
	v_cvt_pk_bf16_f32 v71, v38, v39
	v_mfma_f32_16x16x32_bf16 v[122:125], v[28:31], v[16:19], v[60:63]
	ds_read_b64_tr_b16 v[28:29], v141 offset:53440
	ds_read_b64_tr_b16 v[30:31], v141 offset:58048
	s_waitcnt lgkmcnt(0)
	v_mfma_f32_16x16x32_bf16 v[126:129], v[28:31], v[12:15], v[48:51]
	v_mfma_f32_16x16x32_bf16 v[130:133], v[28:31], v[16:19], v[52:55]
	ds_read_b64_tr_b16 v[28:29], v83 offset:53248
	ds_read_b64_tr_b16 v[30:31], v83 offset:57856
	s_waitcnt lgkmcnt(0)
	v_mfma_f32_16x16x32_bf16 v[34:37], v[28:31], v[12:15], v[40:43]
	v_mfma_f32_16x16x32_bf16 v[66:69], v[28:31], v[16:19], v[44:47]
	v_mfma_f32_16x16x32_bf16 v[62:65], v[0:3], v[70:73], v[4:7]
	v_mfma_f32_16x16x32_bf16 v[28:31], v[0:3], v[74:77], v[8:11]
	ds_read_b64_tr_b16 v[0:1], v141 offset:62464
	s_nop 0
	v_add_u32_e32 v6, v116, v170
	ds_read_b64_tr_b16 v[2:3], v6 offset:49664
	ds_read_b64_tr_b16 v[4:5], v6 offset:49696
	s_waitcnt lgkmcnt(1)
; __device__ __forceinline__ unsigned pk2(float lo, float hi) { f32x2_t v = {lo, hi}; bf16x2_t b = __builtin_convertvector(v, bf16x2_t); return __builtin_bit_cast(unsigned, b); }
; __device__ __forceinline__ float bflo(unsigned u) { return __uint_as_float(u << 16); }
; __device__ __forceinline__ float bfhi(unsigned u) { return __uint_as_float(u & 0xffff0000u); }
; __device__ __forceinline__ float frcp(float x) { return __builtin_amdgcn_rcpf(x); }
; __device__ __forceinline__ float silu(float x) { return x * frcp(1.f + fexp(-x)); }
; __device__ __forceinline__ void mem_unit(const Args& a, int l, LAS unsigned char* lds, int b, int hm, int qb) {
;     ...
; #pragma unroll
;     for (int qt = 0; qt < 2; ++qt) {
;         const float inv = frcp(ol[qt][0]);
;         const size_t row = rowbase + q0 + qt * 16 + fr;
; #pragma unroll
;         for (int dt = 0; dt < 8; ++dt) { const int d0 = dt * 16 + fq * 4;
;             const u32x2 z = *(const u32x2*)(proj + row * NCOL + CZ + 1024 + hm * 128 + d0);
;             u32x2 y; y.x = pk2(o[dt][qt][0] * inv * silu(bflo(z.x)), o[dt][qt][1] * inv * silu(bfhi(z.x))); y.y = pk2(o[dt][qt][2] * inv * silu(bflo(z.y)), o[dt][qt][3] * inv * silu(bfhi(z.y)));
;             *(u32x2*)(proj + row * NCOL + CQM + hm * 128 + d0) = y; }
	v_mfma_f32_16x16x32_bf16 v[78:81], v[0:3], v[70:73], v[20:23]
	v_lshl_add_u64 v[64:65], v[162:163], 0, s[6:7]
	v_lshl_add_u64 v[64:65], v[64:65], 0, v[144:145]
	v_rcp_f32_e32 v62, v62
	v_mfma_f32_16x16x32_bf16 v[30:33], v[0:3], v[74:77], v[24:27]
	ds_read_b64_tr_b16 v[2:3], v141 offset:62496
	s_waitcnt lgkmcnt(0)
	v_mfma_f32_16x16x32_bf16 v[58:61], v[2:5], v[70:73], v[84:87]
	s_nop 7
	v_pk_mul_f32 v[58:59], v[62:63], v[58:59] op_sel_hi:[0,1]
	v_mfma_f32_16x16x32_bf16 v[24:27], v[2:5], v[74:77], v[88:91]
	ds_read_b64_tr_b16 v[0:1], v141 offset:62528
	ds_read_b64_tr_b16 v[2:3], v6 offset:49728
	v_pk_mul_f32 v[60:61], v[62:63], v[60:61] op_sel_hi:[0,1]
	s_waitcnt lgkmcnt(0)
	v_mfma_f32_16x16x32_bf16 v[54:57], v[0:3], v[70:73], v[92:95]
	v_mfma_f32_16x16x32_bf16 v[20:23], v[0:3], v[74:77], v[96:99]
	v_add_u32_e32 v2, v116, v169
	ds_read_b64_tr_b16 v[0:1], v82 offset:62464
	ds_read_b64_tr_b16 v[2:3], v2 offset:49664
	s_waitcnt lgkmcnt(0)
	v_mfma_f32_16x16x32_bf16 v[50:53], v[0:3], v[70:73], v[100:103]
	s_nop 1
	v_mul_f32_e64 v54, v62, v54
	v_mul_f32_e64 v55, v62, v55
	v_pk_mul_f32 v[56:57], v[62:63], v[56:57] op_sel_hi:[0,1]
	s_nop 2
	v_pk_mul_f32 v[50:51], v[62:63], v[50:51] op_sel_hi:[0,1]
	v_mfma_f32_16x16x32_bf16 v[16:19], v[0:3], v[74:77], v[104:107]
	ds_read_b64_tr_b16 v[0:1], v141 offset:62592
	ds_read_b64_tr_b16 v[2:3], v6 offset:49792
	v_pk_mul_f32 v[52:53], v[62:63], v[52:53] op_sel_hi:[0,1]
	s_waitcnt lgkmcnt(0)
	v_mfma_f32_16x16x32_bf16 v[46:49], v[0:3], v[70:73], v[108:111]
	v_mfma_f32_16x16x32_bf16 v[12:15], v[0:3], v[74:77], v[112:115]
	ds_read_b64_tr_b16 v[0:1], v141 offset:62624
	ds_read_b64_tr_b16 v[2:3], v6 offset:49824
	s_nop 4
	v_pk_mul_f32 v[46:47], v[62:63], v[46:47] op_sel_hi:[0,1]
	v_pk_mul_f32 v[48:49], v[62:63], v[48:49] op_sel_hi:[0,1]
	s_waitcnt lgkmcnt(0)
	v_mfma_f32_16x16x32_bf16 v[42:45], v[0:3], v[70:73], v[118:121]
	v_mfma_f32_16x16x32_bf16 v[8:11], v[0:3], v[74:77], v[122:125]
	ds_read_b64_tr_b16 v[0:1], v141 offset:62656
	ds_read_b64_tr_b16 v[2:3], v6 offset:49856
	s_nop 4
	v_pk_mul_f32 v[42:43], v[62:63], v[42:43] op_sel_hi:[0,1]
	v_pk_mul_f32 v[44:45], v[62:63], v[44:45] op_sel_hi:[0,1]
	s_waitcnt lgkmcnt(0)
	v_mfma_f32_16x16x32_bf16 v[38:41], v[0:3], v[70:73], v[126:129]
	v_mfma_f32_16x16x32_bf16 v[4:7], v[0:3], v[74:77], v[130:133]
	v_add_u32_e32 v2, v116, v168
	ds_read_b64_tr_b16 v[0:1], v83 offset:62464
	ds_read_b64_tr_b16 v[2:3], v2 offset:49664
	s_waitcnt lgkmcnt(0)
	v_mfma_f32_16x16x32_bf16 v[34:37], v[0:3], v[70:73], v[34:37]
	s_waitcnt lgkmcnt(0)
	s_barrier
	v_mfma_f32_16x16x32_bf16 v[0:3], v[0:3], v[74:77], v[66:69]
	v_mul_f32_e64 v72, v62, v78
	v_mul_f32_e64 v73, v62, v79
	v_pk_mul_f32 v[38:39], v[62:63], v[38:39] op_sel_hi:[0,1]
	v_pk_mul_f32 v[40:41], v[62:63], v[40:41] op_sel_hi:[0,1]
	v_lshl_add_u64 v[66:67], v[64:65], 0, s[4:5]
	v_add_co_u32_e32 v64, vcc, s26, v64
	v_pk_mul_f32 v[34:35], v[62:63], v[34:35] op_sel_hi:[0,1]
	s_nop 0
	v_addc_co_u32_e32 v65, vcc, 0, v65, vcc
	s_waitcnt vmcnt(0)
	v_mov_b64_e32 v[64:65], v[200:201]
	v_pk_mul_f32 v[36:37], v[62:63], v[36:37] op_sel_hi:[0,1]
	s_waitcnt vmcnt(0)
	v_lshlrev_b32_e32 v68, 16, v64
	v_mul_f32_e32 v29, 0xbfb8aa3b, v68
	v_exp_f32_e32 v29, v29
	v_and_b32_e32 v69, 0xffff0000, v64
	v_lshlrev_b32_e32 v64, 16, v65
	v_and_b32_e32 v65, 0xffff0000, v65
	v_add_f32_e32 v29, 1.0, v29
	v_rcp_f32_e32 v70, v29
	v_mul_f32_e32 v29, 0xbfb8aa3b, v69
	v_exp_f32_e32 v29, v29
	s_nop 0
	v_add_f32_e32 v29, 1.0, v29
	v_rcp_f32_e32 v71, v29
	v_mul_f32_e32 v29, 0xbfb8aa3b, v64
	v_exp_f32_e32 v29, v29
	v_pk_mul_f32 v[68:69], v[70:71], v[68:69]
	s_nop 0
	v_pk_mul_f32 v[68:69], v[72:73], v[68:69]
	v_add_f32_e32 v29, 1.0, v29
	v_rcp_f32_e32 v70, v29
	v_mul_f32_e32 v29, 0xbfb8aa3b, v65
	v_exp_f32_e32 v29, v29
	v_pk_mul_f32 v[72:73], v[62:63], v[80:81] op_sel_hi:[0,1]
	v_cvt_pk_bf16_f32 v68, v68, v69
	v_add_f32_e32 v29, 1.0, v29
	v_rcp_f32_e32 v71, v29
	s_nop 0
	v_pk_mul_f32 v[64:65], v[70:71], v[64:65]
	s_nop 0
	v_pk_mul_f32 v[64:65], v[72:73], v[64:65]
	s_nop 0
	v_cvt_pk_bf16_f32 v69, v64, v65
	v_lshl_add_u64 v[64:65], v[160:161], 0, v[144:145]
	global_store_dwordx2 v[64:65], v[68:69], off offset:2048
	v_mov_b64_e32 v[68:69], v[202:203]
	v_lshlrev_b32_e32 v70, 16, v68
	v_mul_f32_e32 v29, 0xbfb8aa3b, v70
	v_exp_f32_e32 v29, v29
	v_and_b32_e32 v71, 0xffff0000, v68
	v_lshlrev_b32_e32 v68, 16, v69
	v_and_b32_e32 v69, 0xffff0000, v69
	v_add_f32_e32 v29, 1.0, v29
	v_rcp_f32_e32 v72, v29
	v_mul_f32_e32 v29, 0xbfb8aa3b, v71
	v_exp_f32_e32 v29, v29
	s_nop 0
	v_add_f32_e32 v29, 1.0, v29
	v_rcp_f32_e32 v73, v29
	v_mul_f32_e32 v29, 0xbfb8aa3b, v68
	v_exp_f32_e32 v29, v29
	v_pk_mul_f32 v[70:71], v[72:73], v[70:71]
	s_nop 0
	v_pk_mul_f32 v[58:59], v[58:59], v[70:71]
	v_add_f32_e32 v29, 1.0, v29
	v_rcp_f32_e32 v70, v29
	v_mul_f32_e32 v29, 0xbfb8aa3b, v69
	v_exp_f32_e32 v29, v29
	v_cvt_pk_bf16_f32 v58, v58, v59
	v_add_f32_e32 v29, 1.0, v29
	v_rcp_f32_e32 v71, v29
	s_nop 0
	v_pk_mul_f32 v[68:69], v[70:71], v[68:69]
	s_nop 0
	v_pk_mul_f32 v[60:61], v[60:61], v[68:69]
	s_nop 0
	v_cvt_pk_bf16_f32 v59, v60, v61
	global_store_dwordx2 v[64:65], v[58:59], off offset:2080
	v_mov_b64_e32 v[58:59], v[204:205]
	v_lshlrev_b32_e32 v60, 16, v58
	v_mul_f32_e32 v29, 0xbfb8aa3b, v60
	v_exp_f32_e32 v29, v29
	v_and_b32_e32 v61, 0xffff0000, v58
	v_lshlrev_b32_e32 v58, 16, v59
	v_and_b32_e32 v59, 0xffff0000, v59
	v_add_f32_e32 v29, 1.0, v29
	v_rcp_f32_e32 v68, v29
	v_mul_f32_e32 v29, 0xbfb8aa3b, v61
	v_exp_f32_e32 v29, v29
	s_nop 0
	v_add_f32_e32 v29, 1.0, v29
	v_rcp_f32_e32 v69, v29
	v_mul_f32_e32 v29, 0xbfb8aa3b, v58
	v_exp_f32_e32 v29, v29
	v_pk_mul_f32 v[60:61], v[68:69], v[60:61]
	s_nop 0
; __device__ __forceinline__ unsigned pk2(float lo, float hi) { f32x2_t v = {lo, hi}; bf16x2_t b = __builtin_convertvector(v, bf16x2_t); return __builtin_bit_cast(unsigned, b); }
; __device__ __forceinline__ float bflo(unsigned u) { return __uint_as_float(u << 16); }
; __device__ __forceinline__ float bfhi(unsigned u) { return __uint_as_float(u & 0xffff0000u); }
; __device__ __forceinline__ float frcp(float x) { return __builtin_amdgcn_rcpf(x); }
; __device__ __forceinline__ float silu(float x) { return x * frcp(1.f + fexp(-x)); }
; __device__ __forceinline__ void mem_unit(const Args& a, int l, LAS unsigned char* lds, int b, int hm, int qb) {
;     ...
; #pragma unroll
;     for (int qt = 0; qt < 2; ++qt) {
;         const float inv = frcp(ol[qt][0]);
;         const size_t row = rowbase + q0 + qt * 16 + fr;
; #pragma unroll
;         for (int dt = 0; dt < 8; ++dt) { const int d0 = dt * 16 + fq * 4;
;             const u32x2 z = *(const u32x2*)(proj + row * NCOL + CZ + 1024 + hm * 128 + d0);
;             u32x2 y; y.x = pk2(o[dt][qt][0] * inv * silu(bflo(z.x)), o[dt][qt][1] * inv * silu(bfhi(z.x))); y.y = pk2(o[dt][qt][2] * inv * silu(bflo(z.y)), o[dt][qt][3] * inv * silu(bfhi(z.y)));
;             *(u32x2*)(proj + row * NCOL + CQM + hm * 128 + d0) = y; }
	v_pk_mul_f32 v[54:55], v[54:55], v[60:61]
	v_add_f32_e32 v29, 1.0, v29
	v_rcp_f32_e32 v60, v29
	v_mul_f32_e32 v29, 0xbfb8aa3b, v59
	v_exp_f32_e32 v29, v29
	v_cvt_pk_bf16_f32 v54, v54, v55
	v_add_f32_e32 v29, 1.0, v29
	v_rcp_f32_e32 v61, v29
	s_nop 0
	v_pk_mul_f32 v[58:59], v[60:61], v[58:59]
	s_nop 0
	v_pk_mul_f32 v[56:57], v[56:57], v[58:59]
	s_nop 0
	v_cvt_pk_bf16_f32 v55, v56, v57
	global_store_dwordx2 v[64:65], v[54:55], off offset:2112
	v_mov_b64_e32 v[54:55], v[206:207]
	v_lshlrev_b32_e32 v56, 16, v54
	v_mul_f32_e32 v29, 0xbfb8aa3b, v56
	v_exp_f32_e32 v29, v29
	v_and_b32_e32 v57, 0xffff0000, v54
	v_lshlrev_b32_e32 v54, 16, v55
	v_and_b32_e32 v55, 0xffff0000, v55
	v_add_f32_e32 v29, 1.0, v29
	v_rcp_f32_e32 v58, v29
	v_mul_f32_e32 v29, 0xbfb8aa3b, v57
	v_exp_f32_e32 v29, v29
	s_nop 0
	v_add_f32_e32 v29, 1.0, v29
	v_rcp_f32_e32 v59, v29
	v_mul_f32_e32 v29, 0xbfb8aa3b, v54
	v_exp_f32_e32 v29, v29
	v_pk_mul_f32 v[56:57], v[58:59], v[56:57]
	s_nop 0
	v_pk_mul_f32 v[50:51], v[50:51], v[56:57]
	v_add_f32_e32 v29, 1.0, v29
	v_rcp_f32_e32 v56, v29
	v_mul_f32_e32 v29, 0xbfb8aa3b, v55
	v_exp_f32_e32 v29, v29
	v_cvt_pk_bf16_f32 v50, v50, v51
	v_add_f32_e32 v29, 1.0, v29
	v_rcp_f32_e32 v57, v29
	s_nop 0
	v_pk_mul_f32 v[54:55], v[56:57], v[54:55]
	s_nop 0
	v_pk_mul_f32 v[52:53], v[52:53], v[54:55]
	s_nop 0
	v_cvt_pk_bf16_f32 v51, v52, v53
	global_store_dwordx2 v[64:65], v[50:51], off offset:2144
	v_mov_b64_e32 v[50:51], v[208:209]
	v_lshlrev_b32_e32 v52, 16, v50
	v_mul_f32_e32 v29, 0xbfb8aa3b, v52
	v_exp_f32_e32 v29, v29
	v_and_b32_e32 v53, 0xffff0000, v50
	v_lshlrev_b32_e32 v50, 16, v51
	v_and_b32_e32 v51, 0xffff0000, v51
	v_add_f32_e32 v29, 1.0, v29
	v_rcp_f32_e32 v54, v29
	v_mul_f32_e32 v29, 0xbfb8aa3b, v53
	v_exp_f32_e32 v29, v29
	s_nop 0
	v_add_f32_e32 v29, 1.0, v29
	v_rcp_f32_e32 v55, v29
	v_mul_f32_e32 v29, 0xbfb8aa3b, v50
	v_exp_f32_e32 v29, v29
	v_pk_mul_f32 v[52:53], v[54:55], v[52:53]
	s_nop 0
	v_pk_mul_f32 v[46:47], v[46:47], v[52:53]
	v_add_f32_e32 v29, 1.0, v29
	v_rcp_f32_e32 v52, v29
	v_mul_f32_e32 v29, 0xbfb8aa3b, v51
	v_exp_f32_e32 v29, v29
	v_cvt_pk_bf16_f32 v46, v46, v47
	v_add_f32_e32 v29, 1.0, v29
	v_rcp_f32_e32 v53, v29
	s_nop 0
	v_pk_mul_f32 v[50:51], v[52:53], v[50:51]
	s_nop 0
	v_pk_mul_f32 v[48:49], v[48:49], v[50:51]
	s_nop 0
	v_cvt_pk_bf16_f32 v47, v48, v49
	global_store_dwordx2 v[64:65], v[46:47], off offset:2176
	v_mov_b64_e32 v[46:47], v[210:211]
	v_lshlrev_b32_e32 v48, 16, v46
	v_mul_f32_e32 v29, 0xbfb8aa3b, v48
	v_exp_f32_e32 v29, v29
	v_and_b32_e32 v49, 0xffff0000, v46
	v_lshlrev_b32_e32 v46, 16, v47
	v_and_b32_e32 v47, 0xffff0000, v47
	v_add_f32_e32 v29, 1.0, v29
	v_rcp_f32_e32 v50, v29
	v_mul_f32_e32 v29, 0xbfb8aa3b, v49
	v_exp_f32_e32 v29, v29
	s_nop 0
	v_add_f32_e32 v29, 1.0, v29
	v_rcp_f32_e32 v51, v29
	v_mul_f32_e32 v29, 0xbfb8aa3b, v46
	v_exp_f32_e32 v29, v29
	v_pk_mul_f32 v[48:49], v[50:51], v[48:49]
	s_nop 0
	v_pk_mul_f32 v[42:43], v[42:43], v[48:49]
	v_add_f32_e32 v29, 1.0, v29
	v_rcp_f32_e32 v48, v29
	v_mul_f32_e32 v29, 0xbfb8aa3b, v47
	v_exp_f32_e32 v29, v29
	v_cvt_pk_bf16_f32 v42, v42, v43
	v_add_f32_e32 v29, 1.0, v29
	v_rcp_f32_e32 v49, v29
	s_nop 0
	v_pk_mul_f32 v[46:47], v[48:49], v[46:47]
	s_nop 0
	v_pk_mul_f32 v[44:45], v[44:45], v[46:47]
	s_nop 0
	v_cvt_pk_bf16_f32 v43, v44, v45
	global_store_dwordx2 v[64:65], v[42:43], off offset:2208
	v_mov_b64_e32 v[42:43], v[212:213]
	v_lshlrev_b32_e32 v44, 16, v42
	v_mul_f32_e32 v29, 0xbfb8aa3b, v44
	v_exp_f32_e32 v29, v29
	v_and_b32_e32 v45, 0xffff0000, v42
	v_lshlrev_b32_e32 v42, 16, v43
	v_and_b32_e32 v43, 0xffff0000, v43
	v_add_f32_e32 v29, 1.0, v29
	v_rcp_f32_e32 v46, v29
	v_mul_f32_e32 v29, 0xbfb8aa3b, v45
	v_exp_f32_e32 v29, v29
	s_nop 0
	v_add_f32_e32 v29, 1.0, v29
	v_rcp_f32_e32 v47, v29
	v_mul_f32_e32 v29, 0xbfb8aa3b, v42
	v_exp_f32_e32 v29, v29
	v_pk_mul_f32 v[44:45], v[46:47], v[44:45]
	s_nop 0
	v_pk_mul_f32 v[38:39], v[38:39], v[44:45]
	v_add_f32_e32 v29, 1.0, v29
	v_rcp_f32_e32 v44, v29
	v_mul_f32_e32 v29, 0xbfb8aa3b, v43
	v_exp_f32_e32 v29, v29
	v_cvt_pk_bf16_f32 v38, v38, v39
	v_add_f32_e32 v29, 1.0, v29
	v_rcp_f32_e32 v45, v29
	s_nop 0
	v_pk_mul_f32 v[42:43], v[44:45], v[42:43]
	s_nop 0
	v_pk_mul_f32 v[40:41], v[40:41], v[42:43]
	s_nop 0
	v_cvt_pk_bf16_f32 v39, v40, v41
	global_store_dwordx2 v[64:65], v[38:39], off offset:2240
	v_mov_b64_e32 v[38:39], v[214:215]
	v_lshlrev_b32_e32 v40, 16, v38
	v_mul_f32_e32 v29, 0xbfb8aa3b, v40
	v_exp_f32_e32 v29, v29
	v_and_b32_e32 v41, 0xffff0000, v38
	v_lshlrev_b32_e32 v38, 16, v39
	v_and_b32_e32 v39, 0xffff0000, v39
	v_add_f32_e32 v29, 1.0, v29
	v_rcp_f32_e32 v42, v29
	v_mul_f32_e32 v29, 0xbfb8aa3b, v41
	v_exp_f32_e32 v29, v29
	s_nop 0
	v_add_f32_e32 v29, 1.0, v29
	v_rcp_f32_e32 v43, v29
	v_mul_f32_e32 v29, 0xbfb8aa3b, v38
	v_exp_f32_e32 v29, v29
	v_pk_mul_f32 v[40:41], v[42:43], v[40:41]
	s_nop 0
	v_pk_mul_f32 v[34:35], v[34:35], v[40:41]
	v_add_f32_e32 v29, 1.0, v29
	v_rcp_f32_e32 v40, v29
	v_mul_f32_e32 v29, 0xbfb8aa3b, v39
	v_exp_f32_e32 v29, v29
	v_cvt_pk_bf16_f32 v34, v34, v35
	v_add_f32_e32 v29, 1.0, v29
	v_rcp_f32_e32 v41, v29
	s_nop 0
	v_pk_mul_f32 v[38:39], v[40:41], v[38:39]
	s_nop 0
	v_pk_mul_f32 v[36:37], v[36:37], v[38:39]
	s_nop 0
	v_cvt_pk_bf16_f32 v35, v36, v37
	global_store_dwordx2 v[64:65], v[34:35], off offset:2272
	v_rcp_f32_e32 v34, v28
	v_lshl_add_u64 v[28:29], v[158:159], 0, s[6:7]
	v_lshl_add_u64 v[28:29], v[28:29], 0, v[144:145]
	v_lshl_add_u64 v[36:37], v[28:29], 0, s[4:5]
	v_add_co_u32_e32 v28, vcc, s26, v28
	v_pk_mul_f32 v[30:31], v[34:35], v[30:31] op_sel_hi:[0,1]
	s_nop 0
	v_addc_co_u32_e32 v29, vcc, 0, v29, vcc
	v_mov_b64_e32 v[28:29], v[216:217]
; __device__ __forceinline__ unsigned pk2(float lo, float hi) { f32x2_t v = {lo, hi}; bf16x2_t b = __builtin_convertvector(v, bf16x2_t); return __builtin_bit_cast(unsigned, b); }
; __device__ __forceinline__ float bflo(unsigned u) { return __uint_as_float(u << 16); }
; __device__ __forceinline__ float bfhi(unsigned u) { return __uint_as_float(u & 0xffff0000u); }
; __device__ __forceinline__ float frcp(float x) { return __builtin_amdgcn_rcpf(x); }
; __device__ __forceinline__ float silu(float x) { return x * frcp(1.f + fexp(-x)); }
; __device__ __forceinline__ void mem_unit(const Args& a, int l, LAS unsigned char* lds, int b, int hm, int qb) {
;     ...
; #pragma unroll
;     for (int qt = 0; qt < 2; ++qt) {
;         const float inv = frcp(ol[qt][0]);
;         const size_t row = rowbase + q0 + qt * 16 + fr;
; #pragma unroll
;         for (int dt = 0; dt < 8; ++dt) { const int d0 = dt * 16 + fq * 4;
;             const u32x2 z = *(const u32x2*)(proj + row * NCOL + CZ + 1024 + hm * 128 + d0);
;             u32x2 y; y.x = pk2(o[dt][qt][0] * inv * silu(bflo(z.x)), o[dt][qt][1] * inv * silu(bfhi(z.x))); y.y = pk2(o[dt][qt][2] * inv * silu(bflo(z.y)), o[dt][qt][3] * inv * silu(bfhi(z.y)));
;             *(u32x2*)(proj + row * NCOL + CQM + hm * 128 + d0) = y; }
	v_pk_mul_f32 v[32:33], v[34:35], v[32:33] op_sel_hi:[0,1]
	v_pk_mul_f32 v[24:25], v[34:35], v[24:25] op_sel_hi:[0,1]
	v_pk_mul_f32 v[26:27], v[34:35], v[26:27] op_sel_hi:[0,1]
	v_pk_mul_f32 v[20:21], v[34:35], v[20:21] op_sel_hi:[0,1]
	v_pk_mul_f32 v[22:23], v[34:35], v[22:23] op_sel_hi:[0,1]
	v_pk_mul_f32 v[16:17], v[34:35], v[16:17] op_sel_hi:[0,1]
	v_pk_mul_f32 v[18:19], v[34:35], v[18:19] op_sel_hi:[0,1]
	v_pk_mul_f32 v[12:13], v[34:35], v[12:13] op_sel_hi:[0,1]
	v_pk_mul_f32 v[14:15], v[34:35], v[14:15] op_sel_hi:[0,1]
	v_pk_mul_f32 v[8:9], v[34:35], v[8:9] op_sel_hi:[0,1]
	v_pk_mul_f32 v[10:11], v[34:35], v[10:11] op_sel_hi:[0,1]
	v_pk_mul_f32 v[4:5], v[34:35], v[4:5] op_sel_hi:[0,1]
	v_pk_mul_f32 v[6:7], v[34:35], v[6:7] op_sel_hi:[0,1]
	v_pk_mul_f32 v[0:1], v[34:35], v[0:1] op_sel_hi:[0,1]
	v_pk_mul_f32 v[2:3], v[34:35], v[2:3] op_sel_hi:[0,1]
	v_lshlrev_b32_e32 v38, 16, v28
	v_and_b32_e32 v39, 0xffff0000, v28
	v_mul_f32_e32 v28, 0xbfb8aa3b, v38
	v_exp_f32_e32 v28, v28
	s_nop 0
	v_add_f32_e32 v28, 1.0, v28
	v_rcp_f32_e32 v40, v28
	v_mul_f32_e32 v28, 0xbfb8aa3b, v39
	v_exp_f32_e32 v28, v28
	s_nop 0
	v_add_f32_e32 v28, 1.0, v28
	v_rcp_f32_e32 v41, v28
	v_lshlrev_b32_e32 v28, 16, v29
	v_and_b32_e32 v29, 0xffff0000, v29
	v_pk_mul_f32 v[38:39], v[40:41], v[38:39]
	s_nop 0
	v_pk_mul_f32 v[30:31], v[30:31], v[38:39]
	s_nop 0
	v_cvt_pk_bf16_f32 v30, v30, v31
	v_mul_f32_e32 v31, 0xbfb8aa3b, v28
	v_exp_f32_e32 v31, v31
	s_nop 0
	v_add_f32_e32 v31, 1.0, v31
	v_rcp_f32_e32 v38, v31
	v_mul_f32_e32 v31, 0xbfb8aa3b, v29
	v_exp_f32_e32 v31, v31
	s_nop 0
	v_add_f32_e32 v31, 1.0, v31
	v_rcp_f32_e32 v39, v31
	s_nop 0
	v_pk_mul_f32 v[28:29], v[38:39], v[28:29]
	s_nop 0
	v_pk_mul_f32 v[28:29], v[32:33], v[28:29]
	s_nop 0
	v_cvt_pk_bf16_f32 v31, v28, v29
	v_lshl_add_u64 v[28:29], v[156:157], 0, v[144:145]
	global_store_dwordx2 v[28:29], v[30:31], off offset:2048
	v_mov_b64_e32 v[30:31], v[218:219]
	v_lshlrev_b32_e32 v32, 16, v30
	v_and_b32_e32 v33, 0xffff0000, v30
	v_mul_f32_e32 v30, 0xbfb8aa3b, v32
	v_exp_f32_e32 v30, v30
	s_nop 0
	v_add_f32_e32 v30, 1.0, v30
	v_rcp_f32_e32 v38, v30
	v_mul_f32_e32 v30, 0xbfb8aa3b, v33
	v_exp_f32_e32 v30, v30
	s_nop 0
	v_add_f32_e32 v30, 1.0, v30
	v_rcp_f32_e32 v39, v30
	v_lshlrev_b32_e32 v30, 16, v31
	v_and_b32_e32 v31, 0xffff0000, v31
	v_pk_mul_f32 v[32:33], v[38:39], v[32:33]
	s_nop 0
	v_pk_mul_f32 v[24:25], v[24:25], v[32:33]
	s_nop 0
	v_cvt_pk_bf16_f32 v24, v24, v25
	v_mul_f32_e32 v25, 0xbfb8aa3b, v30
	v_exp_f32_e32 v25, v25
	s_nop 0
	v_add_f32_e32 v25, 1.0, v25
	v_rcp_f32_e32 v32, v25
	v_mul_f32_e32 v25, 0xbfb8aa3b, v31
	v_exp_f32_e32 v25, v25
	s_nop 0
	v_add_f32_e32 v25, 1.0, v25
	v_rcp_f32_e32 v33, v25
	s_nop 0
	v_pk_mul_f32 v[30:31], v[32:33], v[30:31]
	s_nop 0
	v_pk_mul_f32 v[26:27], v[26:27], v[30:31]
	s_nop 0
	v_cvt_pk_bf16_f32 v25, v26, v27
	global_store_dwordx2 v[28:29], v[24:25], off offset:2080
	v_mov_b64_e32 v[24:25], v[220:221]
	v_lshlrev_b32_e32 v26, 16, v24
	v_and_b32_e32 v27, 0xffff0000, v24
	v_mul_f32_e32 v24, 0xbfb8aa3b, v26
	v_exp_f32_e32 v24, v24
	s_nop 0
	v_add_f32_e32 v24, 1.0, v24
	v_rcp_f32_e32 v30, v24
	v_mul_f32_e32 v24, 0xbfb8aa3b, v27
	v_exp_f32_e32 v24, v24
	s_nop 0
	v_add_f32_e32 v24, 1.0, v24
	v_rcp_f32_e32 v31, v24
	v_lshlrev_b32_e32 v24, 16, v25
	v_and_b32_e32 v25, 0xffff0000, v25
	v_pk_mul_f32 v[26:27], v[30:31], v[26:27]
	s_nop 0
	v_pk_mul_f32 v[20:21], v[20:21], v[26:27]
	s_nop 0
	v_cvt_pk_bf16_f32 v20, v20, v21
	v_mul_f32_e32 v21, 0xbfb8aa3b, v24
	v_exp_f32_e32 v21, v21
	s_nop 0
	v_add_f32_e32 v21, 1.0, v21
	v_rcp_f32_e32 v26, v21
	v_mul_f32_e32 v21, 0xbfb8aa3b, v25
	v_exp_f32_e32 v21, v21
	s_nop 0
	v_add_f32_e32 v21, 1.0, v21
	v_rcp_f32_e32 v27, v21
	s_nop 0
	v_pk_mul_f32 v[24:25], v[26:27], v[24:25]
	s_nop 0
	v_pk_mul_f32 v[22:23], v[22:23], v[24:25]
	s_nop 0
	v_cvt_pk_bf16_f32 v21, v22, v23
	global_store_dwordx2 v[28:29], v[20:21], off offset:2112
	v_mov_b64_e32 v[20:21], v[222:223]
	v_lshlrev_b32_e32 v22, 16, v20
	v_and_b32_e32 v23, 0xffff0000, v20
	v_mul_f32_e32 v20, 0xbfb8aa3b, v22
	v_exp_f32_e32 v20, v20
	s_nop 0
	v_add_f32_e32 v20, 1.0, v20
	v_rcp_f32_e32 v24, v20
	v_mul_f32_e32 v20, 0xbfb8aa3b, v23
	v_exp_f32_e32 v20, v20
	s_nop 0
	v_add_f32_e32 v20, 1.0, v20
	v_rcp_f32_e32 v25, v20
	v_lshlrev_b32_e32 v20, 16, v21
	v_and_b32_e32 v21, 0xffff0000, v21
	v_pk_mul_f32 v[22:23], v[24:25], v[22:23]
	s_nop 0
	v_pk_mul_f32 v[16:17], v[16:17], v[22:23]
; __device__ __forceinline__ unsigned pk2(float lo, float hi) { f32x2_t v = {lo, hi}; bf16x2_t b = __builtin_convertvector(v, bf16x2_t); return __builtin_bit_cast(unsigned, b); }
; __device__ __forceinline__ float bflo(unsigned u) { return __uint_as_float(u << 16); }
; __device__ __forceinline__ float bfhi(unsigned u) { return __uint_as_float(u & 0xffff0000u); }
; __device__ __forceinline__ float frcp(float x) { return __builtin_amdgcn_rcpf(x); }
; __device__ __forceinline__ float silu(float x) { return x * frcp(1.f + fexp(-x)); }
; __device__ __forceinline__ void mem_unit(const Args& a, int l, LAS unsigned char* lds, int b, int hm, int qb) {
;     ...
; #pragma unroll
;     for (int qt = 0; qt < 2; ++qt) {
;         const float inv = frcp(ol[qt][0]);
;         const size_t row = rowbase + q0 + qt * 16 + fr;
; #pragma unroll
;         for (int dt = 0; dt < 8; ++dt) { const int d0 = dt * 16 + fq * 4;
;             const u32x2 z = *(const u32x2*)(proj + row * NCOL + CZ + 1024 + hm * 128 + d0);
;             u32x2 y; y.x = pk2(o[dt][qt][0] * inv * silu(bflo(z.x)), o[dt][qt][1] * inv * silu(bfhi(z.x))); y.y = pk2(o[dt][qt][2] * inv * silu(bflo(z.y)), o[dt][qt][3] * inv * silu(bfhi(z.y)));
;             *(u32x2*)(proj + row * NCOL + CQM + hm * 128 + d0) = y; }
	s_nop 0
	v_cvt_pk_bf16_f32 v16, v16, v17
	v_mul_f32_e32 v17, 0xbfb8aa3b, v20
	v_exp_f32_e32 v17, v17
	s_nop 0
	v_add_f32_e32 v17, 1.0, v17
	v_rcp_f32_e32 v22, v17
	v_mul_f32_e32 v17, 0xbfb8aa3b, v21
	v_exp_f32_e32 v17, v17
	s_nop 0
	v_add_f32_e32 v17, 1.0, v17
	v_rcp_f32_e32 v23, v17
	s_nop 0
	v_pk_mul_f32 v[20:21], v[22:23], v[20:21]
	s_nop 0
	v_pk_mul_f32 v[18:19], v[18:19], v[20:21]
	s_nop 0
	v_cvt_pk_bf16_f32 v17, v18, v19
	global_store_dwordx2 v[28:29], v[16:17], off offset:2144
	v_mov_b64_e32 v[16:17], v[224:225]
	v_lshlrev_b32_e32 v18, 16, v16
	v_and_b32_e32 v19, 0xffff0000, v16
	v_mul_f32_e32 v16, 0xbfb8aa3b, v18
	v_exp_f32_e32 v16, v16
	s_nop 0
	v_add_f32_e32 v16, 1.0, v16
	v_rcp_f32_e32 v20, v16
	v_mul_f32_e32 v16, 0xbfb8aa3b, v19
	v_exp_f32_e32 v16, v16
	s_nop 0
	v_add_f32_e32 v16, 1.0, v16
	v_rcp_f32_e32 v21, v16
	v_lshlrev_b32_e32 v16, 16, v17
	v_and_b32_e32 v17, 0xffff0000, v17
	v_pk_mul_f32 v[18:19], v[20:21], v[18:19]
	s_nop 0
	v_pk_mul_f32 v[12:13], v[12:13], v[18:19]
	s_nop 0
	v_cvt_pk_bf16_f32 v12, v12, v13
	v_mul_f32_e32 v13, 0xbfb8aa3b, v16
	v_exp_f32_e32 v13, v13
	s_nop 0
	v_add_f32_e32 v13, 1.0, v13
	v_rcp_f32_e32 v18, v13
	v_mul_f32_e32 v13, 0xbfb8aa3b, v17
	v_exp_f32_e32 v13, v13
	s_nop 0
	v_add_f32_e32 v13, 1.0, v13
	v_rcp_f32_e32 v19, v13
	s_nop 0
	v_pk_mul_f32 v[16:17], v[18:19], v[16:17]
	s_nop 0
	v_pk_mul_f32 v[14:15], v[14:15], v[16:17]
	s_nop 0
	v_cvt_pk_bf16_f32 v13, v14, v15
	global_store_dwordx2 v[28:29], v[12:13], off offset:2176
	v_mov_b64_e32 v[12:13], v[226:227]
	v_lshlrev_b32_e32 v14, 16, v12
	v_and_b32_e32 v15, 0xffff0000, v12
	v_mul_f32_e32 v12, 0xbfb8aa3b, v14
	v_exp_f32_e32 v12, v12
	s_nop 0
	v_add_f32_e32 v12, 1.0, v12
	v_rcp_f32_e32 v16, v12
	v_mul_f32_e32 v12, 0xbfb8aa3b, v15
	v_exp_f32_e32 v12, v12
	s_nop 0
	v_add_f32_e32 v12, 1.0, v12
	v_rcp_f32_e32 v17, v12
	v_lshlrev_b32_e32 v12, 16, v13
	v_and_b32_e32 v13, 0xffff0000, v13
	v_pk_mul_f32 v[14:15], v[16:17], v[14:15]
	s_nop 0
	v_pk_mul_f32 v[8:9], v[8:9], v[14:15]
	s_nop 0
	v_cvt_pk_bf16_f32 v8, v8, v9
	v_mul_f32_e32 v9, 0xbfb8aa3b, v12
	v_exp_f32_e32 v9, v9
	s_nop 0
	v_add_f32_e32 v9, 1.0, v9
	v_rcp_f32_e32 v14, v9
	v_mul_f32_e32 v9, 0xbfb8aa3b, v13
	v_exp_f32_e32 v9, v9
	s_nop 0
	v_add_f32_e32 v9, 1.0, v9
	v_rcp_f32_e32 v15, v9
	s_nop 0
	v_pk_mul_f32 v[12:13], v[14:15], v[12:13]
	s_nop 0
	v_pk_mul_f32 v[10:11], v[10:11], v[12:13]
	s_nop 0
	v_cvt_pk_bf16_f32 v9, v10, v11
	global_store_dwordx2 v[28:29], v[8:9], off offset:2208
	v_mov_b64_e32 v[8:9], v[228:229]
	v_lshlrev_b32_e32 v10, 16, v8
	v_and_b32_e32 v11, 0xffff0000, v8
	v_mul_f32_e32 v8, 0xbfb8aa3b, v10
	v_exp_f32_e32 v8, v8
	s_nop 0
	v_add_f32_e32 v8, 1.0, v8
	v_rcp_f32_e32 v12, v8
	v_mul_f32_e32 v8, 0xbfb8aa3b, v11
	v_exp_f32_e32 v8, v8
	s_nop 0
	v_add_f32_e32 v8, 1.0, v8
	v_rcp_f32_e32 v13, v8
	v_lshlrev_b32_e32 v8, 16, v9
	v_and_b32_e32 v9, 0xffff0000, v9
	v_pk_mul_f32 v[10:11], v[12:13], v[10:11]
	s_nop 0
	v_pk_mul_f32 v[4:5], v[4:5], v[10:11]
	s_nop 0
	v_cvt_pk_bf16_f32 v4, v4, v5
	v_mul_f32_e32 v5, 0xbfb8aa3b, v8
	v_exp_f32_e32 v5, v5
	s_nop 0
	v_add_f32_e32 v5, 1.0, v5
	v_rcp_f32_e32 v10, v5
	v_mul_f32_e32 v5, 0xbfb8aa3b, v9
	v_exp_f32_e32 v5, v5
	s_nop 0
	v_add_f32_e32 v5, 1.0, v5
	v_rcp_f32_e32 v11, v5
	s_nop 0
	v_pk_mul_f32 v[8:9], v[10:11], v[8:9]
	s_nop 0
	v_pk_mul_f32 v[6:7], v[6:7], v[8:9]
	s_nop 0
	v_cvt_pk_bf16_f32 v5, v6, v7
	global_store_dwordx2 v[28:29], v[4:5], off offset:2240
	v_mov_b64_e32 v[4:5], v[230:231]
	v_lshlrev_b32_e32 v6, 16, v4
	v_and_b32_e32 v7, 0xffff0000, v4
	v_mul_f32_e32 v4, 0xbfb8aa3b, v6
	v_exp_f32_e32 v4, v4
	s_nop 0
	v_add_f32_e32 v4, 1.0, v4
	v_rcp_f32_e32 v8, v4
	v_mul_f32_e32 v4, 0xbfb8aa3b, v7
	v_exp_f32_e32 v4, v4
	s_nop 0
	v_add_f32_e32 v4, 1.0, v4
	v_rcp_f32_e32 v9, v4
	v_lshlrev_b32_e32 v4, 16, v5
	v_and_b32_e32 v5, 0xffff0000, v5
	v_pk_mul_f32 v[6:7], v[8:9], v[6:7]
	s_nop 0
	v_pk_mul_f32 v[0:1], v[0:1], v[6:7]
	s_nop 0
	v_cvt_pk_bf16_f32 v0, v0, v1
	v_mul_f32_e32 v1, 0xbfb8aa3b, v4
	v_exp_f32_e32 v1, v1
	s_nop 0
	v_add_f32_e32 v1, 1.0, v1
	v_rcp_f32_e32 v6, v1
	v_mul_f32_e32 v1, 0xbfb8aa3b, v5
	v_exp_f32_e32 v1, v1
	s_nop 0
	v_add_f32_e32 v1, 1.0, v1
	v_rcp_f32_e32 v7, v1
	s_nop 0
	v_pk_mul_f32 v[4:5], v[6:7], v[4:5]
	s_nop 0
	v_pk_mul_f32 v[2:3], v[2:3], v[4:5]
	s_nop 0
	v_cvt_pk_bf16_f32 v1, v2, v3
	global_store_dwordx2 v[28:29], v[0:1], off offset:2272
	s_cbranch_scc0 .LBB0_519
